# prompt attention softmax: O rescale as 64 v_mul_f32 instead of 32 v_pk_mul_f32, skipped when alpha==1 in every lane (exact)
# speedup vs baseline: 1.0271x; 1.0005x over previous
; template <int DK, int DV, int KT, bool SAMPLE>
; DI void attn_item(CP c, int l, int qb, int h, unsigned char* sm) {
;     ...
;     for (int j = 0; j < nj; ++j) {
;         const int kt = 2 * j + g;
;         lds_barrier();
;         if (!SAMPLE) {
; #pragma unroll
;             for (int i = 0; i < 6; ++i) *(u32x4*)(Ks + lkey * QS + ls0 * 8 + i * 32) = kreg[i];
; #pragma unroll
;             for (int i = 0; i < 4; ++i) *(u32x4*)(Vs + ldv * VS + lv0 * 8 + i * 16) = vreg[i];
;         } else {
;             const int k0 = kt * 32;
;             for (int v = gt; v < 32 * 40; v += 256) { const int key = v / 40, s = v % 40, kk = k0 + key; u32x4 o = (u32x4){0u, 0u, 0u, 0u};
;                 if (kk < 2048) { const float* src = s < 32 ? c->in[I_CLAT] + ((size_t)(l * 32 + b) * 2048 + kk) * 256 + s * 8 : c->in[I_CKPE] + ((size_t)(l * 32 + b) * 2048 + kk) * 64 + (s - 32) * 8;
;                     const f32x4 a = *(const f32x4*)src, bq = *(const f32x4*)(src + 4); o.x = pk2(a[0], a[1]); o.y = pk2(a[2], a[3]); o.z = pk2(bq[0], bq[1]); o.w = pk2(bq[2], bq[3]); }
;                 else if (kk < 2064) { const int rr = MP + b * 16 + (kk - 2048); o = *(const u32x4*)(s < 32 ? LATg + (size_t)rr * 256 + s * 8 : KPEg + (size_t)rr * 64 + (s - 32) * 8); }
;                 *(u32x4*)(Ks + key * QS + s * 8) = o; }
;             for (int v = gt; v < 256 * 4; v += 256) { const int dv = v >> 2, s = v & 3; u32x4 o = (u32x4){0u, 0u, 0u, 0u};
;                 if (k0 < LTS) o = *(const u32x4*)(LTg + ((size_t)b * 256 + dv) * LTS + k0 + s * 8);
;                 *(u32x4*)(Vs + dv * VS + s * 8) = o; }
;         }
;         lds_barrier();
;         if (!SAMPLE) { if (j + 1 < nj) ATT_ISSUE(kt + 2); }
;         const bool active = SAMPLE ? (wave_on && kt * 32 < 2064) : (kt <= qc);
;         if (active) {
;             f32x16 S[NMT];
; #pragma unroll
;             for (int mt = 0; mt < NMT; ++mt)
; #pragma unroll
;                 for (int i = 0; i < 16; ++i) S[mt][i] = 0.f;
;             {
;                 constexpr int NKP = DK / 32;
;                 bf16x8 Kf[2][2 * NMT]; bf16x8 Ql[2][2];
; #pragma unroll
;                 for (int e = 0; e < 2; ++e) {
; #pragma unroll
;                     for (int mt = 0; mt < NMT; ++mt) Kf[0][e * NMT + mt] = *(const bf16x8*)(Ks + (32 * mt + l31) * QS + 16 * e + 8 * hh);
.LBB0_647:
	s_waitcnt lgkmcnt(0)
	s_barrier
	s_waitcnt vmcnt(9)
	ds_write_b128 v178, v[112:115] offset:51200
	s_waitcnt vmcnt(8)
	ds_write_b128 v178, v[116:119] offset:51264
	s_waitcnt vmcnt(7)
	ds_write_b128 v178, v[120:123] offset:51328
	s_waitcnt vmcnt(6)
	ds_write_b128 v178, v[124:127] offset:51392
	s_waitcnt vmcnt(5)
	ds_write_b128 v178, v[128:131] offset:51456
	s_waitcnt vmcnt(4)
	ds_write_b128 v178, v[132:135] offset:51520
	s_waitcnt vmcnt(3)
	ds_write2_b64 v179, v[136:137], v[138:139] offset0:0 offset1:2
	s_waitcnt vmcnt(2)
	ds_write2_b64 v179, v[140:141], v[142:143] offset0:4 offset1:6
	s_waitcnt vmcnt(1)
	ds_write2_b64 v179, v[144:145], v[146:147] offset0:8 offset1:10
	s_waitcnt vmcnt(0)
	ds_write2_b64 v179, v[148:149], v[150:151] offset0:12 offset1:14
	s_waitcnt lgkmcnt(0)
	s_barrier
	v_cmp_lt_u32_e32 vcc, s14, v171
	v_add_u32_e32 v2, 2, v246
	s_and_saveexec_b64 s[16:17], vcc
	s_cbranch_execz .LBB0_649
	v_lshl_add_u64 v[156:157], v[156:157], 0, s[40:41]
	v_lshl_add_u64 v[158:159], v[158:159], 0, s[42:43]
	v_lshl_add_u64 v[164:165], v[164:165], 0, s[88:89]
	ds_read_b128 v[4:7], v180 offset:51200
	ds_read_b128 v[8:11], v180 offset:51232
	ds_read_b128 v[12:15], v180 offset:64000
	ds_read_b128 v[184:187], v180 offset:64032
	ds_read_b128 v[218:221], v180 offset:51264
	ds_read_b128 v[222:225], v180 offset:51296
	ds_read_b128 v[226:229], v180 offset:64064
	ds_read_b128 v[230:233], v180 offset:64096
	s_waitcnt lgkmcnt(5)
	v_mfma_f32_32x32x16_bf16 v[96:111], v[4:7], v[80:83], 0
	v_mfma_f32_32x32x16_bf16 v[80:95], v[12:15], v[80:83], 0
	global_load_dwordx4 v[112:115], v[156:157], off
	s_waitcnt lgkmcnt(4)
	v_mfma_f32_32x32x16_bf16 v[96:111], v[8:11], v[214:217], v[96:111]
	v_mfma_f32_32x32x16_bf16 v[80:95], v[184:187], v[214:217], v[80:95]
	ds_read_b128 v[4:7], v180 offset:51328
	ds_read_b128 v[8:11], v180 offset:51360
	ds_read_b128 v[12:15], v180 offset:64128
	ds_read_b128 v[184:187], v180 offset:64160
	ds_read_b128 v[214:217], v181 offset:128
	ds_read_b128 v[242:245], v181 offset:160
	s_waitcnt lgkmcnt(7)
	v_mfma_f32_32x32x16_bf16 v[96:111], v[218:221], v[234:237], v[96:111]
	v_mfma_f32_32x32x16_bf16 v[80:95], v[226:229], v[234:237], v[80:95]
	global_load_dwordx4 v[116:119], v[156:157], off offset:64
	s_waitcnt lgkmcnt(6)
	v_mfma_f32_32x32x16_bf16 v[96:111], v[222:225], v[238:241], v[96:111]
	v_mfma_f32_32x32x16_bf16 v[80:95], v[230:233], v[238:241], v[80:95]
	ds_read_b128 v[218:221], v180 offset:51392
	ds_read_b128 v[222:225], v180 offset:51424
	ds_read_b128 v[226:229], v180 offset:64192
	ds_read_b128 v[230:233], v180 offset:64224
	ds_read_b128 v[234:237], v181 offset:192
	ds_read_b128 v[238:241], v181 offset:224
	s_waitcnt lgkmcnt(7)
	v_mfma_f32_32x32x16_bf16 v[96:111], v[4:7], v[214:217], v[96:111]
	v_mfma_f32_32x32x16_bf16 v[80:95], v[12:15], v[214:217], v[80:95]
	global_load_dwordx4 v[120:123], v[156:157], off offset:128
	s_waitcnt lgkmcnt(6)
	v_mfma_f32_32x32x16_bf16 v[96:111], v[8:11], v[242:245], v[96:111]
	v_mfma_f32_32x32x16_bf16 v[80:95], v[184:187], v[242:245], v[80:95]
	ds_read_b128 v[4:7], v180 offset:51456
	ds_read_b128 v[8:11], v180 offset:51488
	ds_read_b128 v[12:15], v180 offset:64256
	ds_read_b128 v[184:187], v180 offset:64288
	ds_read_b128 v[214:217], v181 offset:256
	ds_read_b128 v[242:245], v181 offset:288
	s_waitcnt lgkmcnt(7)
	v_mfma_f32_32x32x16_bf16 v[96:111], v[218:221], v[234:237], v[96:111]
	v_mfma_f32_32x32x16_bf16 v[80:95], v[226:229], v[234:237], v[80:95]
	global_load_dwordx4 v[124:127], v[156:157], off offset:192
	s_waitcnt lgkmcnt(6)
	v_mfma_f32_32x32x16_bf16 v[96:111], v[222:225], v[238:241], v[96:111]
	v_mfma_f32_32x32x16_bf16 v[80:95], v[230:233], v[238:241], v[80:95]
	ds_read_b128 v[218:221], v180 offset:51520
	ds_read_b128 v[222:225], v180 offset:51552
	ds_read_b128 v[226:229], v180 offset:64320
	ds_read_b128 v[230:233], v180 offset:64352
	ds_read_b128 v[234:237], v181 offset:320
	ds_read_b128 v[238:241], v181 offset:352
	s_waitcnt lgkmcnt(7)
	v_mfma_f32_32x32x16_bf16 v[96:111], v[4:7], v[214:217], v[96:111]
	v_mfma_f32_32x32x16_bf16 v[80:95], v[12:15], v[214:217], v[80:95]
	global_load_dwordx4 v[128:131], v[158:159], off
	s_waitcnt lgkmcnt(6)
	v_mfma_f32_32x32x16_bf16 v[96:111], v[8:11], v[242:245], v[96:111]
	v_mfma_f32_32x32x16_bf16 v[80:95], v[184:187], v[242:245], v[80:95]
	s_waitcnt lgkmcnt(1)
	v_mfma_f32_32x32x16_bf16 v[96:111], v[218:221], v[234:237], v[96:111]
	v_mfma_f32_32x32x16_bf16 v[80:95], v[226:229], v[234:237], v[80:95]
	global_load_dwordx4 v[132:135], v[158:159], off offset:64
	s_waitcnt lgkmcnt(0)
; template <int DK, int DV, int KT, bool SAMPLE>
; DI void attn_item(CP c, int l, int qb, int h, unsigned char* sm) {
;     ...
;             float mloc = -INFINITY;
; #pragma unroll
;             for (int mt = 0; mt < NMT; ++mt)
; #pragma unroll
;                 for (int i = 0; i < 16; ++i) { float s = S[mt][i] * scale;
;                     if (SAMPLE) { const int key = kt * KT + 32 * mt + (i & 3) + 8 * (i >> 2) + 4 * hh; if (key >= 2064) s = -INFINITY; }
;                     S[mt][i] = s; mloc = fmaxf(mloc, s); }
;             mloc = fmaxf(mloc, __shfl_xor(mloc, 32));
;             const float mnew = fmaxf(m_run, mloc); const float alpha = __builtin_amdgcn_exp2f(m_run - mnew); float psum = 0.f;
; #pragma unroll
;             for (int mt = 0; mt < NMT; ++mt)
; #pragma unroll
;                 for (int i = 0; i < 16; ++i) { const float p = __builtin_amdgcn_exp2f(S[mt][i] - mnew); S[mt][i] = p; psum += p; }
;             l_run = l_run * alpha + psum; m_run = mnew;
; #pragma unroll
;             for (int d = 0; d < NDT; ++d) Oacc[d] = Oacc[d] * alpha;
	v_mfma_f32_32x32x16_bf16 v[96:111], v[222:225], v[238:241], v[96:111]
	v_mfma_f32_32x32x16_bf16 v[80:95], v[230:233], v[238:241], v[80:95]
	s_nop 10
	s_mov_b32 s18, 0xff800000
	v_max3_f32 v0, v96, s18, v97
	v_max3_f32 v0, v0, v98, v99
	v_max3_f32 v0, v0, v100, v101
	v_max3_f32 v0, v0, v102, v103
	v_max3_f32 v0, v0, v104, v105
	v_max3_f32 v0, v0, v106, v107
	v_max3_f32 v0, v0, v108, v109
	v_max3_f32 v0, v0, v110, v111
	v_max3_f32 v0, v0, v80, v81
	v_max3_f32 v0, v0, v82, v83
	v_max3_f32 v0, v0, v84, v85
	v_max3_f32 v0, v0, v86, v87
	v_max3_f32 v0, v0, v88, v89
	v_max3_f32 v0, v0, v90, v91
	v_max3_f32 v0, v0, v92, v93
	v_max3_f32 v0, v0, v94, v95
	s_mov_b32 s18, 0x3dd53b94
	v_mul_f32_e32 v0, 0x3dd53b94, v0
	v_add_u32_e32 v226, 0x6000, v182
	v_mov_b32_e32 v3, v0
	v_mov_b32_e32 v4, v0
	v_add_u32_e32 v227, 0x7000, v182
	v_add_u32_e32 v228, 0x8800, v182
	v_permlane32_swap_b32_e32 v3, v4
	v_add_u32_e32 v229, 0x9800, v182
	v_max3_f32 v3, v183, v3, v4
	v_fma_f32 v4, v96, s18, -v3
	v_sub_f32_e32 v0, v183, v3
	v_exp_f32_e32 v183, v4
	v_fma_f32 v4, v97, s18, -v3
	v_exp_f32_e32 v184, v4
	v_fma_f32 v4, v98, s18, -v3
	v_exp_f32_e32 v185, v4
	v_fma_f32 v4, v99, s18, -v3
	v_exp_f32_e32 v186, v4
	v_fma_f32 v5, v100, s18, -v3
	v_add_f32_e32 v4, 0, v183
	v_exp_f32_e32 v187, v5
	v_fma_f32 v5, v101, s18, -v3
	v_add_f32_e32 v4, v184, v4
	v_exp_f32_e32 v192, v5
	v_fma_f32 v5, v102, s18, -v3
	v_add_f32_e32 v4, v185, v4
	v_exp_f32_e32 v193, v5
	v_fma_f32 v5, v103, s18, -v3
	v_add_f32_e32 v4, v186, v4
	v_exp_f32_e32 v103, v5
	v_fma_f32 v5, v104, s18, -v3
	v_add_f32_e32 v4, v187, v4
	v_exp_f32_e32 v104, v5
	v_fma_f32 v5, v105, s18, -v3
	v_add_f32_e32 v4, v192, v4
	v_exp_f32_e32 v105, v5
	v_fma_f32 v5, v106, s18, -v3
	v_add_f32_e32 v4, v193, v4
	v_exp_f32_e32 v106, v5
	v_fma_f32 v5, v107, s18, -v3
	v_add_f32_e32 v4, v103, v4
	v_exp_f32_e32 v107, v5
	v_fma_f32 v5, v108, s18, -v3
	v_add_f32_e32 v4, v104, v4
	v_exp_f32_e32 v108, v5
	v_fma_f32 v5, v109, s18, -v3
	v_add_f32_e32 v4, v105, v4
	v_exp_f32_e32 v109, v5
	v_fma_f32 v5, v110, s18, -v3
	v_add_f32_e32 v4, v106, v4
	v_exp_f32_e32 v110, v5
	v_fma_f32 v5, v111, s18, -v3
	v_add_f32_e32 v4, v107, v4
	v_exp_f32_e32 v111, v5
	v_fma_f32 v5, v80, s18, -v3
	v_add_f32_e32 v4, v108, v4
	v_exp_f32_e32 v204, v5
	v_fma_f32 v5, v81, s18, -v3
	v_add_f32_e32 v4, v109, v4
	v_exp_f32_e32 v205, v5
	v_fma_f32 v5, v82, s18, -v3
	v_add_f32_e32 v4, v110, v4
	v_exp_f32_e32 v206, v5
	v_fma_f32 v5, v83, s18, -v3
	v_add_f32_e32 v4, v111, v4
	v_exp_f32_e32 v207, v5
	v_fma_f32 v5, v84, s18, -v3
	v_exp_f32_e32 v213, v5
	v_fma_f32 v5, v85, s18, -v3
	v_add_f32_e32 v4, v204, v4
	v_exp_f32_e32 v214, v5
	v_fma_f32 v5, v86, s18, -v3
	v_add_f32_e32 v4, v205, v4
	v_exp_f32_e32 v215, v5
	v_fma_f32 v5, v87, s18, -v3
	v_add_f32_e32 v4, v206, v4
	v_exp_f32_e32 v216, v5
	v_fma_f32 v5, v88, s18, -v3
	v_add_f32_e32 v4, v207, v4
	v_exp_f32_e32 v217, v5
	v_fma_f32 v5, v89, s18, -v3
	v_add_f32_e32 v4, v213, v4
	v_exp_f32_e32 v218, v5
	v_fma_f32 v5, v90, s18, -v3
	v_add_f32_e32 v4, v214, v4
	v_exp_f32_e32 v219, v5
	v_fma_f32 v5, v91, s18, -v3
	v_add_f32_e32 v4, v215, v4
	v_exp_f32_e32 v220, v5
	v_fma_f32 v5, v92, s18, -v3
	v_add_f32_e32 v4, v216, v4
	v_exp_f32_e32 v221, v5
	v_fma_f32 v5, v93, s18, -v3
	v_add_f32_e32 v4, v217, v4
	v_exp_f32_e32 v222, v5
	v_fma_f32 v5, v94, s18, -v3
	v_add_f32_e32 v4, v218, v4
	v_exp_f32_e32 v223, v5
	v_fma_f32 v5, v95, s18, -v3
	v_add_f32_e32 v4, v219, v4
	v_exp_f32_e32 v224, v5
	v_add_f32_e32 v4, v220, v4
	v_add_f32_e32 v4, v221, v4
	v_add_f32_e32 v4, v222, v4
	v_add_f32_e32 v4, v223, v4
	v_add_f32_e32 v225, v224, v4
	ds_read_b128 v[4:7], v226 offset:1024
	ds_read_b128 v[8:11], v226 offset:1056
	ds_read_b128 v[12:15], v227 offset:1536
	ds_read_b128 v[80:83], v228
	ds_read_b128 v[84:87], v229 offset:512
	ds_read_b128 v[88:91], v227 offset:1568
	ds_read_b128 v[92:95], v228 offset:32
	ds_read_b128 v[96:99], v229 offset:544
	v_exp_f32_e32 v0, v0
	v_cvt_pk_bf16_f32 v100, v183, v184
	v_cvt_pk_bf16_f32 v101, v185, v186
	v_cvt_pk_bf16_f32 v102, v187, v192
	v_cmp_neq_f32_e32 vcc, 1.0, v0
	s_cbranch_vccz .Lresc_skip1
	v_mul_f32_e32 v78, v0, v78
	v_mul_f32_e32 v79, v0, v79
	v_mul_f32_e32 v76, v0, v76
	v_mul_f32_e32 v77, v0, v77
	v_mul_f32_e32 v74, v0, v74
	v_mul_f32_e32 v75, v0, v75
	v_mul_f32_e32 v72, v0, v72
	v_mul_f32_e32 v73, v0, v73
	v_mul_f32_e32 v70, v0, v70
	v_mul_f32_e32 v71, v0, v71
	v_mul_f32_e32 v68, v0, v68
	v_mul_f32_e32 v69, v0, v69
	v_mul_f32_e32 v66, v0, v66
	v_mul_f32_e32 v67, v0, v67
	v_mul_f32_e32 v64, v0, v64
	v_mul_f32_e32 v65, v0, v65
	v_mul_f32_e32 v62, v0, v62
	v_mul_f32_e32 v63, v0, v63
	v_mul_f32_e32 v60, v0, v60
	v_mul_f32_e32 v61, v0, v61
	v_mul_f32_e32 v58, v0, v58
	v_mul_f32_e32 v59, v0, v59
	v_mul_f32_e32 v56, v0, v56
	v_mul_f32_e32 v57, v0, v57
	v_mul_f32_e32 v54, v0, v54
	v_mul_f32_e32 v55, v0, v55
	v_mul_f32_e32 v52, v0, v52
	v_mul_f32_e32 v53, v0, v53
	v_mul_f32_e32 v50, v0, v50
	v_mul_f32_e32 v51, v0, v51
	v_mul_f32_e32 v48, v0, v48
	v_mul_f32_e32 v49, v0, v49
	v_mul_f32_e32 v46, v0, v46
	v_mul_f32_e32 v47, v0, v47
	v_mul_f32_e32 v44, v0, v44
	v_mul_f32_e32 v45, v0, v45
	v_mul_f32_e32 v42, v0, v42
	v_mul_f32_e32 v43, v0, v43
	v_mul_f32_e32 v40, v0, v40
	v_mul_f32_e32 v41, v0, v41
	v_mul_f32_e32 v38, v0, v38
	v_mul_f32_e32 v39, v0, v39
	v_mul_f32_e32 v36, v0, v36
	v_mul_f32_e32 v37, v0, v37
	v_mul_f32_e32 v34, v0, v34
	v_mul_f32_e32 v35, v0, v35
	v_mul_f32_e32 v32, v0, v32
	v_mul_f32_e32 v33, v0, v33
	v_mul_f32_e32 v30, v0, v30
	v_mul_f32_e32 v31, v0, v31
	v_mul_f32_e32 v28, v0, v28
	v_mul_f32_e32 v29, v0, v29
	v_mul_f32_e32 v26, v0, v26
	v_mul_f32_e32 v27, v0, v27
	v_mul_f32_e32 v24, v0, v24
	v_mul_f32_e32 v25, v0, v25
	v_mul_f32_e32 v22, v0, v22
	v_mul_f32_e32 v23, v0, v23
	v_mul_f32_e32 v20, v0, v20
	v_mul_f32_e32 v21, v0, v21
	v_mul_f32_e32 v18, v0, v18
	v_mul_f32_e32 v19, v0, v19
	v_mul_f32_e32 v16, v0, v16
	v_mul_f32_e32 v17, v0, v17
; template <int DK, int DV, int KT, bool SAMPLE>
; DI void attn_item(CP c, int l, int qb, int h, unsigned char* sm) {
;     ...
;             {
;                 constexpr int NKP = DK / 32;
;                 bf16x8 Kf[2][2 * NMT]; bf16x8 Ql[2][2];
; #pragma unroll
;                 for (int e = 0; e < 2; ++e) {
; #pragma unroll
;                     for (int mt = 0; mt < NMT; ++mt) Kf[0][e * NMT + mt] = *(const bf16x8*)(Ks + (32 * mt + l31) * QS + 16 * e + 8 * hh);
;                     if (!QREG) Ql[0][e] = *(const bf16x8*)(Qs + (32 * wq + l31) * QS + 16 * e + 8 * hh); }
; #pragma unroll
;                 for (int kp = 0; kp < NKP; ++kp) {
;                     if (kp + 1 < NKP) {
; #pragma unroll
;                         for (int e = 0; e < 2; ++e) {
; #pragma unroll
;                             for (int mt = 0; mt < NMT; ++mt) Kf[(kp + 1) & 1][e * NMT + mt] = *(const bf16x8*)(Ks + (32 * mt + l31) * QS + 16 * (2 * kp + 2 + e) + 8 * hh);
;                             if (!QREG) Ql[(kp + 1) & 1][e] = *(const bf16x8*)(Qs + (32 * wq + l31) * QS + 16 * (2 * kp + 2 + e) + 8 * hh); } }
;                     __builtin_amdgcn_sched_barrier(0);
; #pragma unroll
;                     for (int e = 0; e < 2; ++e)
; #pragma unroll
;                         for (int mt = 0; mt < NMT; ++mt) S[mt] = __builtin_amdgcn_mfma_f32_32x32x16_bf16(Kf[kp & 1][e * NMT + mt], !QREG ? Ql[kp & 1][e] : Qf[QREG ? 2 * kp + e : 0], S[mt], 0, 0, 0);
;                     __builtin_amdgcn_sched_barrier(0);
;     ...
;                 for (int gi = 0; gi < NG; ++gi) { const int kg = gi / NDB, db = gi % NDB, mt = kg >> 1, s2 = kg & 1;
;                     if (gi + 1 < NG) ATT_LDV((gi + 1) & 1, gi + 1);
;                     u32x4 pw; pw.x = pk2(S[mt][8 * s2 + 0], S[mt][8 * s2 + 1]); pw.y = pk2(S[mt][8 * s2 + 2], S[mt][8 * s2 + 3]);
;                     pw.z = pk2(S[mt][8 * s2 + 4], S[mt][8 * s2 + 5]); pw.w = pk2(S[mt][8 * s2 + 6], S[mt][8 * s2 + 7]);
;                     const bf16x8 pf = __builtin_bit_cast(bf16x8, pw);
;                     __builtin_amdgcn_sched_barrier(0);
; #pragma unroll
;                     for (int d = 0; d < 4; ++d) Oacc[4 * db + d] = __builtin_amdgcn_mfma_f32_32x32x16_bf16(__builtin_bit_cast(bf16x8, Vf[gi & 1][d]), pf, Oacc[4 * db + d], 0, 0, 0);
;                     __builtin_amdgcn_sched_barrier(0);
;                 }
.Lresc_skip1:
	v_cvt_pk_bf16_f32 v103, v193, v103
	s_waitcnt lgkmcnt(7)
	s_nop 0
	v_mfma_f32_32x32x16_bf16 v[64:79], v[4:7], v[100:103], v[64:79]
	s_waitcnt lgkmcnt(5)
	v_mfma_f32_32x32x16_bf16 v[48:63], v[12:15], v[100:103], v[48:63]
	global_load_dwordx4 v[136:139], v[164:165], off
	s_waitcnt lgkmcnt(4)
	v_mfma_f32_32x32x16_bf16 v[32:47], v[80:83], v[100:103], v[32:47]
	s_waitcnt lgkmcnt(3)
	v_mfma_f32_32x32x16_bf16 v[16:31], v[84:87], v[100:103], v[16:31]
	ds_read_b128 v[4:7], v226 offset:1088
	ds_read_b128 v[12:15], v227 offset:1600
	ds_read_b128 v[80:83], v228 offset:64
	ds_read_b128 v[84:87], v229 offset:576
	v_cvt_pk_bf16_f32 v100, v104, v105
	v_cvt_pk_bf16_f32 v101, v106, v107
	v_cvt_pk_bf16_f32 v102, v108, v109
	v_cvt_pk_bf16_f32 v103, v110, v111
	s_nop 1
	v_mfma_f32_32x32x16_bf16 v[64:79], v[8:11], v[100:103], v[64:79]
	s_waitcnt lgkmcnt(6)
	v_mfma_f32_32x32x16_bf16 v[48:63], v[88:91], v[100:103], v[48:63]
	global_load_dwordx4 v[140:143], v[164:165], off offset:32
	s_waitcnt lgkmcnt(5)
	v_mfma_f32_32x32x16_bf16 v[32:47], v[92:95], v[100:103], v[32:47]
	s_waitcnt lgkmcnt(4)
	v_mfma_f32_32x32x16_bf16 v[16:31], v[96:99], v[100:103], v[16:31]
	ds_read_b128 v[8:11], v226 offset:1120
	ds_read_b128 v[88:91], v227 offset:1632
	ds_read_b128 v[92:95], v228 offset:96
	ds_read_b128 v[96:99], v229 offset:608
	v_cvt_pk_bf16_f32 v100, v204, v205
	v_cvt_pk_bf16_f32 v101, v206, v207
	v_cvt_pk_bf16_f32 v102, v213, v214
	v_cvt_pk_bf16_f32 v103, v215, v216
	s_waitcnt lgkmcnt(7)
	s_nop 0
	v_mfma_f32_32x32x16_bf16 v[64:79], v[4:7], v[100:103], v[64:79]
	s_waitcnt lgkmcnt(6)
	v_mfma_f32_32x32x16_bf16 v[48:63], v[12:15], v[100:103], v[48:63]
	global_load_dwordx4 v[144:147], v[164:165], off offset:64
	s_waitcnt lgkmcnt(5)
	v_mfma_f32_32x32x16_bf16 v[32:47], v[80:83], v[100:103], v[32:47]
	s_waitcnt lgkmcnt(4)
	v_mfma_f32_32x32x16_bf16 v[16:31], v[84:87], v[100:103], v[16:31]
	v_cvt_pk_bf16_f32 v4, v217, v218
	v_cvt_pk_bf16_f32 v5, v219, v220
	v_cvt_pk_bf16_f32 v6, v221, v222
	v_cvt_pk_bf16_f32 v7, v223, v224
	s_waitcnt lgkmcnt(3)
	s_nop 0
	v_mfma_f32_32x32x16_bf16 v[64:79], v[8:11], v[4:7], v[64:79]
	s_waitcnt lgkmcnt(2)
	v_mfma_f32_32x32x16_bf16 v[48:63], v[88:91], v[4:7], v[48:63]
	global_load_dwordx4 v[148:151], v[164:165], off offset:96
	s_waitcnt lgkmcnt(1)
	v_mfma_f32_32x32x16_bf16 v[32:47], v[92:95], v[4:7], v[32:47]
	s_waitcnt lgkmcnt(0)
	v_mfma_f32_32x32x16_bf16 v[16:31], v[96:99], v[4:7], v[16:31]
	ds_read_b128 v[80:83], v181
	ds_read_b128 v[214:217], v181 offset:32
	ds_read_b128 v[234:237], v181 offset:64
	ds_read_b128 v[238:241], v181 offset:96
	v_fmac_f32_e32 v225, v177, v0
	v_mov_b32_e32 v177, v225
	v_mov_b32_e32 v183, v3
	s_branch .LBB0_646
.LBB0_649:
	s_or_b64 exec, exec, s[16:17]
	v_cmp_le_i32_e32 vcc, v246, v175
	s_and_saveexec_b64 s[16:17], vcc
	s_cbranch_execz .LBB0_646
	ds_read_b128 v[4:7], v180 offset:51200
	ds_read_b128 v[8:11], v180 offset:51232
	ds_read_b128 v[12:15], v180 offset:64000
	ds_read_b128 v[184:187], v180 offset:64032
	ds_read_b128 v[218:221], v180 offset:51264
	ds_read_b128 v[222:225], v180 offset:51296
	ds_read_b128 v[226:229], v180 offset:64064
	ds_read_b128 v[230:233], v180 offset:64096
	s_waitcnt lgkmcnt(5)
	v_mfma_f32_32x32x16_bf16 v[96:111], v[4:7], v[80:83], 0
	v_mfma_f32_32x32x16_bf16 v[80:95], v[12:15], v[80:83], 0
	s_waitcnt lgkmcnt(4)
	v_mfma_f32_32x32x16_bf16 v[96:111], v[8:11], v[214:217], v[96:111]
	v_mfma_f32_32x32x16_bf16 v[80:95], v[184:187], v[214:217], v[80:95]
	ds_read_b128 v[4:7], v180 offset:51328
	ds_read_b128 v[8:11], v180 offset:51360
	ds_read_b128 v[12:15], v180 offset:64128
	ds_read_b128 v[184:187], v180 offset:64160
	ds_read_b128 v[214:217], v181 offset:128
	ds_read_b128 v[242:245], v181 offset:160
	s_waitcnt lgkmcnt(7)
	v_mfma_f32_32x32x16_bf16 v[96:111], v[218:221], v[234:237], v[96:111]
	v_mfma_f32_32x32x16_bf16 v[80:95], v[226:229], v[234:237], v[80:95]
	s_waitcnt lgkmcnt(6)
	v_mfma_f32_32x32x16_bf16 v[96:111], v[222:225], v[238:241], v[96:111]
	v_mfma_f32_32x32x16_bf16 v[80:95], v[230:233], v[238:241], v[80:95]
	ds_read_b128 v[218:221], v180 offset:51392
	ds_read_b128 v[222:225], v180 offset:51424
	ds_read_b128 v[226:229], v180 offset:64192
	ds_read_b128 v[230:233], v180 offset:64224
	ds_read_b128 v[234:237], v181 offset:192
	ds_read_b128 v[238:241], v181 offset:224
	s_waitcnt lgkmcnt(7)
	v_mfma_f32_32x32x16_bf16 v[96:111], v[4:7], v[214:217], v[96:111]
	v_mfma_f32_32x32x16_bf16 v[80:95], v[12:15], v[214:217], v[80:95]
	s_waitcnt lgkmcnt(6)
	v_mfma_f32_32x32x16_bf16 v[96:111], v[8:11], v[242:245], v[96:111]
	v_mfma_f32_32x32x16_bf16 v[80:95], v[184:187], v[242:245], v[80:95]
	ds_read_b128 v[4:7], v180 offset:51456
	ds_read_b128 v[8:11], v180 offset:51488
	ds_read_b128 v[12:15], v180 offset:64256
	ds_read_b128 v[184:187], v180 offset:64288
	ds_read_b128 v[214:217], v181 offset:256
	ds_read_b128 v[242:245], v181 offset:288
	s_waitcnt lgkmcnt(7)
	v_mfma_f32_32x32x16_bf16 v[96:111], v[218:221], v[234:237], v[96:111]
	v_mfma_f32_32x32x16_bf16 v[80:95], v[226:229], v[234:237], v[80:95]
	s_waitcnt lgkmcnt(6)
	v_mfma_f32_32x32x16_bf16 v[96:111], v[222:225], v[238:241], v[96:111]
	v_mfma_f32_32x32x16_bf16 v[80:95], v[230:233], v[238:241], v[80:95]
	ds_read_b128 v[218:221], v180 offset:51520
	ds_read_b128 v[222:225], v180 offset:51552
	ds_read_b128 v[226:229], v180 offset:64320
	ds_read_b128 v[230:233], v180 offset:64352
	ds_read_b128 v[234:237], v181 offset:320
	ds_read_b128 v[238:241], v181 offset:352
	s_waitcnt lgkmcnt(7)
	v_mfma_f32_32x32x16_bf16 v[96:111], v[4:7], v[214:217], v[96:111]
	v_mfma_f32_32x32x16_bf16 v[80:95], v[12:15], v[214:217], v[80:95]
	s_waitcnt lgkmcnt(6)
; template <int DK, int DV, int KT, bool SAMPLE>
; DI void attn_item(CP c, int l, int qb, int h, unsigned char* sm) {
;     ...
;             float mloc = -INFINITY;
; #pragma unroll
;             for (int mt = 0; mt < NMT; ++mt)
; #pragma unroll
;                 for (int i = 0; i < 16; ++i) { float s = S[mt][i] * scale;
;                     if (SAMPLE) { const int key = kt * KT + 32 * mt + (i & 3) + 8 * (i >> 2) + 4 * hh; if (key >= 2064) s = -INFINITY; }
;                     S[mt][i] = s; mloc = fmaxf(mloc, s); }
;             mloc = fmaxf(mloc, __shfl_xor(mloc, 32));
;             const float mnew = fmaxf(m_run, mloc); const float alpha = __builtin_amdgcn_exp2f(m_run - mnew); float psum = 0.f;
; #pragma unroll
;             for (int mt = 0; mt < NMT; ++mt)
; #pragma unroll
;                 for (int i = 0; i < 16; ++i) { const float p = __builtin_amdgcn_exp2f(S[mt][i] - mnew); S[mt][i] = p; psum += p; }
;             l_run = l_run * alpha + psum; m_run = mnew;
; #pragma unroll
;             for (int d = 0; d < NDT; ++d) Oacc[d] = Oacc[d] * alpha;
	v_mfma_f32_32x32x16_bf16 v[96:111], v[8:11], v[242:245], v[96:111]
	v_mfma_f32_32x32x16_bf16 v[80:95], v[184:187], v[242:245], v[80:95]
	s_waitcnt lgkmcnt(1)
	v_mfma_f32_32x32x16_bf16 v[96:111], v[218:221], v[234:237], v[96:111]
	v_mfma_f32_32x32x16_bf16 v[80:95], v[226:229], v[234:237], v[80:95]
	s_waitcnt lgkmcnt(0)
	v_mfma_f32_32x32x16_bf16 v[96:111], v[222:225], v[238:241], v[96:111]
	v_mfma_f32_32x32x16_bf16 v[80:95], v[230:233], v[238:241], v[80:95]
	s_nop 10
	s_mov_b32 s18, 0xff800000
	v_max3_f32 v0, v96, s18, v97
	v_max3_f32 v0, v0, v98, v99
	v_max3_f32 v0, v0, v100, v101
	v_max3_f32 v0, v0, v102, v103
	v_max3_f32 v0, v0, v104, v105
	v_max3_f32 v0, v0, v106, v107
	v_max3_f32 v0, v0, v108, v109
	v_max3_f32 v0, v0, v110, v111
	v_max3_f32 v0, v0, v80, v81
	v_max3_f32 v0, v0, v82, v83
	v_max3_f32 v0, v0, v84, v85
	v_max3_f32 v0, v0, v86, v87
	v_max3_f32 v0, v0, v88, v89
	v_max3_f32 v0, v0, v90, v91
	v_max3_f32 v0, v0, v92, v93
	v_max3_f32 v0, v0, v94, v95
	s_mov_b32 s18, 0x3dd53b94
	v_mul_f32_e32 v0, 0x3dd53b94, v0
	v_add_u32_e32 v226, 0x6000, v182
	v_mov_b32_e32 v3, v0
	v_mov_b32_e32 v4, v0
	v_add_u32_e32 v227, 0x7000, v182
	v_add_u32_e32 v228, 0x8800, v182
	v_permlane32_swap_b32_e32 v3, v4
	v_add_u32_e32 v229, 0x9800, v182
	v_max3_f32 v3, v183, v3, v4
	v_fma_f32 v4, v96, s18, -v3
	v_sub_f32_e32 v0, v183, v3
	v_exp_f32_e32 v183, v4
	v_fma_f32 v4, v97, s18, -v3
	v_exp_f32_e32 v184, v4
	v_fma_f32 v4, v98, s18, -v3
	v_exp_f32_e32 v185, v4
	v_fma_f32 v4, v99, s18, -v3
	v_exp_f32_e32 v186, v4
	v_fma_f32 v5, v100, s18, -v3
	v_add_f32_e32 v4, 0, v183
	v_exp_f32_e32 v187, v5
	v_fma_f32 v5, v101, s18, -v3
	v_add_f32_e32 v4, v184, v4
	v_exp_f32_e32 v192, v5
	v_fma_f32 v5, v102, s18, -v3
	v_add_f32_e32 v4, v185, v4
	v_exp_f32_e32 v193, v5
	v_fma_f32 v5, v103, s18, -v3
	v_add_f32_e32 v4, v186, v4
	v_exp_f32_e32 v103, v5
	v_fma_f32 v5, v104, s18, -v3
	v_add_f32_e32 v4, v187, v4
	v_exp_f32_e32 v104, v5
	v_fma_f32 v5, v105, s18, -v3
	v_add_f32_e32 v4, v192, v4
	v_exp_f32_e32 v105, v5
	v_fma_f32 v5, v106, s18, -v3
	v_add_f32_e32 v4, v193, v4
	v_exp_f32_e32 v106, v5
	v_fma_f32 v5, v107, s18, -v3
	v_add_f32_e32 v4, v103, v4
	v_exp_f32_e32 v107, v5
	v_fma_f32 v5, v108, s18, -v3
	v_add_f32_e32 v4, v104, v4
	v_exp_f32_e32 v108, v5
	v_fma_f32 v5, v109, s18, -v3
	v_add_f32_e32 v4, v105, v4
	v_exp_f32_e32 v109, v5
	v_fma_f32 v5, v110, s18, -v3
	v_add_f32_e32 v4, v106, v4
	v_exp_f32_e32 v110, v5
	v_fma_f32 v5, v111, s18, -v3
	v_add_f32_e32 v4, v107, v4
	v_exp_f32_e32 v111, v5
	v_fma_f32 v5, v80, s18, -v3
	v_add_f32_e32 v4, v108, v4
	v_exp_f32_e32 v204, v5
	v_fma_f32 v5, v81, s18, -v3
	v_add_f32_e32 v4, v109, v4
	v_exp_f32_e32 v205, v5
	v_fma_f32 v5, v82, s18, -v3
	v_add_f32_e32 v4, v110, v4
	v_exp_f32_e32 v206, v5
	v_fma_f32 v5, v83, s18, -v3
	v_add_f32_e32 v4, v111, v4
	v_exp_f32_e32 v207, v5
	v_fma_f32 v5, v84, s18, -v3
	v_exp_f32_e32 v213, v5
	v_fma_f32 v5, v85, s18, -v3
	v_add_f32_e32 v4, v204, v4
	v_exp_f32_e32 v214, v5
	v_fma_f32 v5, v86, s18, -v3
	v_add_f32_e32 v4, v205, v4
	v_exp_f32_e32 v215, v5
	v_fma_f32 v5, v87, s18, -v3
	v_add_f32_e32 v4, v206, v4
	v_exp_f32_e32 v216, v5
	v_fma_f32 v5, v88, s18, -v3
	v_add_f32_e32 v4, v207, v4
	v_exp_f32_e32 v217, v5
	v_fma_f32 v5, v89, s18, -v3
	v_add_f32_e32 v4, v213, v4
	v_exp_f32_e32 v218, v5
	v_fma_f32 v5, v90, s18, -v3
	v_add_f32_e32 v4, v214, v4
	v_exp_f32_e32 v219, v5
	v_fma_f32 v5, v91, s18, -v3
	v_add_f32_e32 v4, v215, v4
	v_exp_f32_e32 v220, v5
	v_fma_f32 v5, v92, s18, -v3
	v_add_f32_e32 v4, v216, v4
	v_exp_f32_e32 v221, v5
	v_fma_f32 v5, v93, s18, -v3
	v_add_f32_e32 v4, v217, v4
	v_exp_f32_e32 v222, v5
	v_fma_f32 v5, v94, s18, -v3
	v_add_f32_e32 v4, v218, v4
	v_exp_f32_e32 v223, v5
	v_fma_f32 v5, v95, s18, -v3
	v_add_f32_e32 v4, v219, v4
	v_exp_f32_e32 v224, v5
	v_add_f32_e32 v4, v220, v4
	v_add_f32_e32 v4, v221, v4
	v_add_f32_e32 v4, v222, v4
	v_add_f32_e32 v4, v223, v4
	v_add_f32_e32 v225, v224, v4
	ds_read_b128 v[4:7], v226 offset:1024
	ds_read_b128 v[8:11], v226 offset:1056
	ds_read_b128 v[12:15], v227 offset:1536
	ds_read_b128 v[80:83], v228
	ds_read_b128 v[84:87], v229 offset:512
	ds_read_b128 v[88:91], v227 offset:1568
	ds_read_b128 v[92:95], v228 offset:32
	ds_read_b128 v[96:99], v229 offset:544
	v_exp_f32_e32 v0, v0
	v_cvt_pk_bf16_f32 v100, v183, v184
	v_cvt_pk_bf16_f32 v101, v185, v186
	v_cvt_pk_bf16_f32 v102, v187, v192
	v_cmp_neq_f32_e32 vcc, 1.0, v0
	s_cbranch_vccz .Lresc_skip2
	v_mul_f32_e32 v78, v0, v78
	v_mul_f32_e32 v79, v0, v79
	v_mul_f32_e32 v76, v0, v76
	v_mul_f32_e32 v77, v0, v77
	v_mul_f32_e32 v74, v0, v74
	v_mul_f32_e32 v75, v0, v75
	v_mul_f32_e32 v72, v0, v72
	v_mul_f32_e32 v73, v0, v73
	v_mul_f32_e32 v70, v0, v70
	v_mul_f32_e32 v71, v0, v71
	v_mul_f32_e32 v68, v0, v68
	v_mul_f32_e32 v69, v0, v69
	v_mul_f32_e32 v66, v0, v66
	v_mul_f32_e32 v67, v0, v67
	v_mul_f32_e32 v64, v0, v64
	v_mul_f32_e32 v65, v0, v65
	v_mul_f32_e32 v62, v0, v62
	v_mul_f32_e32 v63, v0, v63
	v_mul_f32_e32 v60, v0, v60
	v_mul_f32_e32 v61, v0, v61
	v_mul_f32_e32 v58, v0, v58
	v_mul_f32_e32 v59, v0, v59
	v_mul_f32_e32 v56, v0, v56
	v_mul_f32_e32 v57, v0, v57
	v_mul_f32_e32 v54, v0, v54
	v_mul_f32_e32 v55, v0, v55
	v_mul_f32_e32 v52, v0, v52
	v_mul_f32_e32 v53, v0, v53
	v_mul_f32_e32 v50, v0, v50
	v_mul_f32_e32 v51, v0, v51
	v_mul_f32_e32 v48, v0, v48
	v_mul_f32_e32 v49, v0, v49
	v_mul_f32_e32 v46, v0, v46
	v_mul_f32_e32 v47, v0, v47
	v_mul_f32_e32 v44, v0, v44
	v_mul_f32_e32 v45, v0, v45
	v_mul_f32_e32 v42, v0, v42
	v_mul_f32_e32 v43, v0, v43
	v_mul_f32_e32 v40, v0, v40
	v_mul_f32_e32 v41, v0, v41
	v_mul_f32_e32 v38, v0, v38
	v_mul_f32_e32 v39, v0, v39
	v_mul_f32_e32 v36, v0, v36
	v_mul_f32_e32 v37, v0, v37
	v_mul_f32_e32 v34, v0, v34
	v_mul_f32_e32 v35, v0, v35
	v_mul_f32_e32 v32, v0, v32
	v_mul_f32_e32 v33, v0, v33
	v_mul_f32_e32 v30, v0, v30
	v_mul_f32_e32 v31, v0, v31
	v_mul_f32_e32 v28, v0, v28
	v_mul_f32_e32 v29, v0, v29
	v_mul_f32_e32 v26, v0, v26
	v_mul_f32_e32 v27, v0, v27
	v_mul_f32_e32 v24, v0, v24
	v_mul_f32_e32 v25, v0, v25
	v_mul_f32_e32 v22, v0, v22
	v_mul_f32_e32 v23, v0, v23
	v_mul_f32_e32 v20, v0, v20
	v_mul_f32_e32 v21, v0, v21
	v_mul_f32_e32 v18, v0, v18
	v_mul_f32_e32 v19, v0, v19
	v_mul_f32_e32 v16, v0, v16
	v_mul_f32_e32 v17, v0, v17
; DI unsigned pk2(float lo, float hi) { const hwf2_t v = {lo, hi}; const hwbf2_t b = __builtin_convertvector(v, hwbf2_t); return __builtin_bit_cast(unsigned, b); }
; #define ATT_LDV(buf, gi) do { const int _kg = (gi) / NDB, _db = (gi) % NDB; _Pragma("unroll") for (int d = 0; d < 4; ++d) { const bf16_t* vp = Vs + (32 * (4 * _db + d) + l31) * VS + 16 * _kg + 4 * hh; \
;                         const u32x2 lo = *(const u32x2*)vp, hi = *(const u32x2*)(vp + 8); Vf[buf][d].x = lo.x; Vf[buf][d].y = lo.y; Vf[buf][d].z = hi.x; Vf[buf][d].w = hi.y; } } while (0)
; template <int DK, int DV, int KT, bool SAMPLE>
; DI void attn_item(CP c, int l, int qb, int h, unsigned char* sm) {
;     ...
;                 for (int gi = 0; gi < NG; ++gi) { const int kg = gi / NDB, db = gi % NDB, mt = kg >> 1, s2 = kg & 1;
;                     if (gi + 1 < NG) ATT_LDV((gi + 1) & 1, gi + 1);
;                     u32x4 pw; pw.x = pk2(S[mt][8 * s2 + 0], S[mt][8 * s2 + 1]); pw.y = pk2(S[mt][8 * s2 + 2], S[mt][8 * s2 + 3]);
;                     pw.z = pk2(S[mt][8 * s2 + 4], S[mt][8 * s2 + 5]); pw.w = pk2(S[mt][8 * s2 + 6], S[mt][8 * s2 + 7]);
;                     const bf16x8 pf = __builtin_bit_cast(bf16x8, pw);
;                     __builtin_amdgcn_sched_barrier(0);
; #pragma unroll
;                     for (int d = 0; d < 4; ++d) Oacc[4 * db + d] = __builtin_amdgcn_mfma_f32_32x32x16_bf16(__builtin_bit_cast(bf16x8, Vf[gi & 1][d]), pf, Oacc[4 * db + d], 0, 0, 0);
;                     __builtin_amdgcn_sched_barrier(0);
;                 }
.Lresc_skip2:
	v_cvt_pk_bf16_f32 v103, v193, v103
	s_waitcnt lgkmcnt(7)
	s_nop 0
	v_mfma_f32_32x32x16_bf16 v[64:79], v[4:7], v[100:103], v[64:79]
	s_waitcnt lgkmcnt(5)
	v_mfma_f32_32x32x16_bf16 v[48:63], v[12:15], v[100:103], v[48:63]
	s_waitcnt lgkmcnt(4)
	v_mfma_f32_32x32x16_bf16 v[32:47], v[80:83], v[100:103], v[32:47]
	s_waitcnt lgkmcnt(3)
	v_mfma_f32_32x32x16_bf16 v[16:31], v[84:87], v[100:103], v[16:31]
	ds_read_b128 v[4:7], v226 offset:1088
	ds_read_b128 v[12:15], v227 offset:1600
	ds_read_b128 v[80:83], v228 offset:64
	ds_read_b128 v[84:87], v229 offset:576
	v_cvt_pk_bf16_f32 v100, v104, v105
	v_cvt_pk_bf16_f32 v101, v106, v107
	v_cvt_pk_bf16_f32 v102, v108, v109
	v_cvt_pk_bf16_f32 v103, v110, v111
	s_nop 1
	v_mfma_f32_32x32x16_bf16 v[64:79], v[8:11], v[100:103], v[64:79]
	s_waitcnt lgkmcnt(6)
	v_mfma_f32_32x32x16_bf16 v[48:63], v[88:91], v[100:103], v[48:63]
	s_waitcnt lgkmcnt(5)
	v_mfma_f32_32x32x16_bf16 v[32:47], v[92:95], v[100:103], v[32:47]
	s_waitcnt lgkmcnt(4)
	v_mfma_f32_32x32x16_bf16 v[16:31], v[96:99], v[100:103], v[16:31]
	ds_read_b128 v[8:11], v226 offset:1120
	ds_read_b128 v[88:91], v227 offset:1632
	ds_read_b128 v[92:95], v228 offset:96
	ds_read_b128 v[96:99], v229 offset:608
	v_cvt_pk_bf16_f32 v100, v204, v205
	v_cvt_pk_bf16_f32 v101, v206, v207
	v_cvt_pk_bf16_f32 v102, v213, v214
	v_cvt_pk_bf16_f32 v103, v215, v216
	s_waitcnt lgkmcnt(7)
	s_nop 0
	v_mfma_f32_32x32x16_bf16 v[64:79], v[4:7], v[100:103], v[64:79]
	s_waitcnt lgkmcnt(6)
	v_mfma_f32_32x32x16_bf16 v[48:63], v[12:15], v[100:103], v[48:63]
	s_waitcnt lgkmcnt(5)
	v_mfma_f32_32x32x16_bf16 v[32:47], v[80:83], v[100:103], v[32:47]
	s_waitcnt lgkmcnt(4)
	v_mfma_f32_32x32x16_bf16 v[16:31], v[84:87], v[100:103], v[16:31]
	v_cvt_pk_bf16_f32 v4, v217, v218
	v_cvt_pk_bf16_f32 v5, v219, v220
	v_cvt_pk_bf16_f32 v6, v221, v222
	v_cvt_pk_bf16_f32 v7, v223, v224
	s_waitcnt lgkmcnt(3)
	s_nop 0
	v_mfma_f32_32x32x16_bf16 v[64:79], v[8:11], v[4:7], v[64:79]
	s_waitcnt lgkmcnt(2)
	v_mfma_f32_32x32x16_bf16 v[48:63], v[88:91], v[4:7], v[48:63]
	s_waitcnt lgkmcnt(1)
	v_mfma_f32_32x32x16_bf16 v[32:47], v[92:95], v[4:7], v[32:47]
	s_waitcnt lgkmcnt(0)
	v_mfma_f32_32x32x16_bf16 v[16:31], v[96:99], v[4:7], v[16:31]
	ds_read_b128 v[80:83], v181
	ds_read_b128 v[214:217], v181 offset:32
	ds_read_b128 v[234:237], v181 offset:64
	ds_read_b128 v[238:241], v181 offset:96
	v_fmac_f32_e32 v225, v177, v0
	v_mov_b32_e32 v177, v225
	v_mov_b32_e32 v183, v3
	s_branch .LBB0_646
